# wave-group stagger in the barrier-free MT=2 phaseA unit loop: waves 4..7 start ~7us later so epilogue VALU overlaps the SIMD partner's weight streaming
# baseline (speedup 1.0000x reference)
; DI int otid() { int t = threadIdx.x; asm volatile("" : "+v"(t)); return t; }
; template <int K, class Epi>
; DI void gemm64_res(const bf16_t* A, int lda, const bf16_t* Wp, int NU, unsigned char* lds, const Epi& epi) {
;     constexpr int KS = K / 16, PD = 4, LD = K * 2 + 16, SEGS = K / 8, NIT = 64 * SEGS / NTHR;
;     const int tid = otid(), wave = __builtin_amdgcn_readfirstlane(tid >> 6), lane = tid & 63, r = lane & 31, h = lane >> 5;
;     const u32x4* Bw = (const u32x4*)Wp;
;     const size_t kstr = (size_t)NU * NT * 64;
;     const int rot = ((blockIdx.x >> 3) * (KS / 32)) & (KS - 1);
;     __syncthreads();
; #pragma unroll
;     for (int i0 = 0; i0 < NIT; i0 += 8) {
;         u32x4 t8[8];
; #pragma unroll
;         for (int i = 0; i < 8; ++i) { const int idx = (i0 + i) * NTHR + tid, row = idx / SEGS, seg = idx % SEGS; t8[i] = *(const u32x4*)(A + (row * lda + seg * 8)); }
; #pragma unroll
;         for (int i = 0; i < 8; ++i) { const int idx = (i0 + i) * NTHR + tid, row = idx / SEGS, seg = idx % SEGS; *(u32x4*)(lds + row * LD + seg * 16) = t8[i]; }
;     }
.LBB0_885:
	v_readlane_b32 s0, v255, 52
	v_readlane_b32 s1, v255, 53
	s_and_b64 vcc, exec, s[0:1]
	s_cbranch_vccnz .LBB0_860
	v_mov_b32_e32 v0, v176
	s_lshl_b64 s[0:1], s[66:67], 11
	v_ashrrev_i32_e32 v2, 31, v0
	v_lshrrev_b32_e32 v2, 25, v2
	v_add_u32_e32 v6, 0x200, v0
	v_add_u32_e32 v2, v0, v2
	v_ashrrev_i32_e32 v7, 31, v6
	v_readlane_b32 s2, v253, 16
	v_ashrrev_i32_e32 v34, 7, v2
	v_and_b32_e32 v2, 0xfffff80, v2
	v_lshrrev_b32_e32 v7, 25, v7
	v_add_u32_e32 v10, 0x400, v0
	s_add_u32 s0, s2, s0
	v_readlane_b32 s2, v253, 17
	v_sub_u32_e32 v35, v0, v2
	v_lshlrev_b32_e32 v2, 3, v0
	v_add_u32_e32 v7, v6, v7
	v_ashrrev_i32_e32 v11, 31, v10
	s_addc_u32 s1, s2, s1
	v_ashrrev_i32_e32 v3, 31, v2
	v_ashrrev_i32_e32 v36, 7, v7
	v_and_b32_e32 v7, 0xfffff80, v7
	v_lshrrev_b32_e32 v11, 25, v11
	v_add_u32_e32 v14, 0x600, v0
	v_lshl_add_u64 v[2:3], v[2:3], 1, s[0:1]
	v_sub_u32_e32 v37, v6, v7
	v_lshlrev_b32_e32 v6, 3, v6
	v_add_u32_e32 v11, v10, v11
	v_ashrrev_i32_e32 v15, 31, v14
	s_barrier
	global_load_dwordx4 v[2:5], v[2:3], off
	v_ashrrev_i32_e32 v7, 31, v6
	v_ashrrev_i32_e32 v38, 7, v11
	v_and_b32_e32 v11, 0xfffff80, v11
	v_lshrrev_b32_e32 v15, 25, v15
	v_add_u32_e32 v18, 0x800, v0
	v_lshl_add_u64 v[6:7], v[6:7], 1, s[0:1]
	v_sub_u32_e32 v39, v10, v11
	v_lshlrev_b32_e32 v10, 3, v10
	v_add_u32_e32 v15, v14, v15
	v_ashrrev_i32_e32 v19, 31, v18
	global_load_dwordx4 v[6:9], v[6:7], off
	v_ashrrev_i32_e32 v11, 31, v10
	v_ashrrev_i32_e32 v40, 7, v15
	v_and_b32_e32 v15, 0xfffff80, v15
	v_lshrrev_b32_e32 v19, 25, v19
	v_add_u32_e32 v22, 0xa00, v0
	v_lshl_add_u64 v[10:11], v[10:11], 1, s[0:1]
	v_sub_u32_e32 v41, v14, v15
	v_lshlrev_b32_e32 v14, 3, v14
	v_add_u32_e32 v19, v18, v19
	v_ashrrev_i32_e32 v23, 31, v22
	global_load_dwordx4 v[10:13], v[10:11], off
	v_ashrrev_i32_e32 v15, 31, v14
	v_ashrrev_i32_e32 v42, 7, v19
	v_and_b32_e32 v19, 0xfffff80, v19
	v_lshrrev_b32_e32 v23, 25, v23
	v_add_u32_e32 v26, 0xc00, v0
	v_lshl_add_u64 v[14:15], v[14:15], 1, s[0:1]
	v_sub_u32_e32 v43, v18, v19
	v_lshlrev_b32_e32 v18, 3, v18
	v_add_u32_e32 v23, v22, v23
	v_ashrrev_i32_e32 v27, 31, v26
	global_load_dwordx4 v[14:17], v[14:15], off
	v_ashrrev_i32_e32 v19, 31, v18
	v_ashrrev_i32_e32 v44, 7, v23
	v_and_b32_e32 v23, 0xfffff80, v23
	v_lshrrev_b32_e32 v27, 25, v27
	v_add_u32_e32 v30, 0xe00, v0
	v_lshl_add_u64 v[18:19], v[18:19], 1, s[0:1]
	v_sub_u32_e32 v45, v22, v23
	v_lshlrev_b32_e32 v22, 3, v22
	v_add_u32_e32 v27, v26, v27
	v_ashrrev_i32_e32 v31, 31, v30
	global_load_dwordx4 v[18:21], v[18:19], off
	v_ashrrev_i32_e32 v23, 31, v22
	v_ashrrev_i32_e32 v46, 7, v27
	v_and_b32_e32 v27, 0xfffff80, v27
	v_lshrrev_b32_e32 v31, 25, v31
	v_lshl_add_u64 v[22:23], v[22:23], 1, s[0:1]
	v_sub_u32_e32 v47, v26, v27
	v_lshlrev_b32_e32 v26, 3, v26
	v_add_u32_e32 v31, v30, v31
	global_load_dwordx4 v[22:25], v[22:23], off
	v_ashrrev_i32_e32 v27, 31, v26
	v_ashrrev_i32_e32 v48, 7, v31
	v_and_b32_e32 v31, 0xfffff80, v31
	v_lshl_add_u64 v[26:27], v[26:27], 1, s[0:1]
	v_sub_u32_e32 v49, v30, v31
	v_lshlrev_b32_e32 v30, 3, v30
	global_load_dwordx4 v[26:29], v[26:27], off
	v_ashrrev_i32_e32 v31, 31, v30
	v_lshl_add_u64 v[30:31], v[30:31], 1, s[0:1]
	global_load_dwordx4 v[30:33], v[30:31], off
	v_mul_lo_u32 v34, v34, s16
	v_lshl_add_u32 v34, v35, 4, v34
	v_readfirstlane_b32 s2, v0
	s_ashr_i32 s28, s2, 6
	s_cmpk_gt_i32 s28, 0x43
	s_waitcnt vmcnt(7)
	ds_write_b128 v34, v[2:5]
	v_mul_lo_u32 v2, v36, s16
	v_lshl_add_u32 v2, v37, 4, v2
	s_waitcnt vmcnt(6)
	ds_write_b128 v2, v[6:9]
	v_mul_lo_u32 v2, v38, s16
	v_lshl_add_u32 v2, v39, 4, v2
	v_add_u32_e32 v6, 0x1200, v0
	v_ashrrev_i32_e32 v7, 31, v6
	v_lshrrev_b32_e32 v7, 25, v7
	v_add_u32_e32 v7, v6, v7
	v_ashrrev_i32_e32 v36, 7, v7
	v_and_b32_e32 v7, 0xfffff80, v7
	v_sub_u32_e32 v37, v6, v7
	v_lshlrev_b32_e32 v6, 3, v6
	s_waitcnt vmcnt(5)
	ds_write_b128 v2, v[10:13]
	v_mul_lo_u32 v2, v40, s16
	v_lshl_add_u32 v2, v41, 4, v2
	v_add_u32_e32 v10, 0x1400, v0
	v_ashrrev_i32_e32 v11, 31, v10
	v_lshrrev_b32_e32 v11, 25, v11
	v_add_u32_e32 v11, v10, v11
	v_ashrrev_i32_e32 v7, 31, v6
	v_ashrrev_i32_e32 v38, 7, v11
	v_and_b32_e32 v11, 0xfffff80, v11
	v_lshl_add_u64 v[6:7], v[6:7], 1, s[0:1]
	s_waitcnt vmcnt(4)
	ds_write_b128 v2, v[14:17]
	v_mul_lo_u32 v2, v42, s16
	v_lshl_add_u32 v2, v43, 4, v2
	v_add_u32_e32 v14, 0x1600, v0
	v_ashrrev_i32_e32 v15, 31, v14
	v_lshrrev_b32_e32 v15, 25, v15
	v_sub_u32_e32 v39, v10, v11
	v_lshlrev_b32_e32 v10, 3, v10
	v_add_u32_e32 v15, v14, v15
	global_load_dwordx4 v[6:9], v[6:7], off
	v_ashrrev_i32_e32 v11, 31, v10
	s_waitcnt vmcnt(4)
; template <int K, class Epi>
; DI void gemm64_res(const bf16_t* A, int lda, const bf16_t* Wp, int NU, unsigned char* lds, const Epi& epi) {
;     ...
;     for (int i0 = 0; i0 < NIT; i0 += 8) {
;         u32x4 t8[8];
; #pragma unroll
;         for (int i = 0; i < 8; ++i) { const int idx = (i0 + i) * NTHR + tid, row = idx / SEGS, seg = idx % SEGS; t8[i] = *(const u32x4*)(A + (row * lda + seg * 8)); }
; #pragma unroll
;         for (int i = 0; i < 8; ++i) { const int idx = (i0 + i) * NTHR + tid, row = idx / SEGS, seg = idx % SEGS; *(u32x4*)(lds + row * LD + seg * 16) = t8[i]; }
;     }
;     __syncthreads();
;     const unsigned char* ab = lds + r * LD + 16 * h;
; #pragma unroll 1
;     for (int unit = wave; unit < NU; unit += NWAVE) {
;         const u32x4* bp = Bw + (size_t)(unit * NT) * 64 + lane;
	ds_write_b128 v2, v[18:21]
	v_mul_lo_u32 v2, v44, s16
	v_lshl_add_u32 v2, v45, 4, v2
	v_add_u32_e32 v18, 0x1800, v0
	v_ashrrev_i32_e32 v19, 31, v18
	v_ashrrev_i32_e32 v40, 7, v15
	v_and_b32_e32 v15, 0xfffff80, v15
	v_lshrrev_b32_e32 v19, 25, v19
	v_lshl_add_u64 v[10:11], v[10:11], 1, s[0:1]
	s_waitcnt vmcnt(3)
	ds_write_b128 v2, v[22:25]
	v_mul_lo_u32 v2, v46, s16
	v_lshl_add_u32 v2, v47, 4, v2
	v_add_u32_e32 v22, 0x1a00, v0
	v_sub_u32_e32 v41, v14, v15
	v_lshlrev_b32_e32 v14, 3, v14
	v_add_u32_e32 v19, v18, v19
	s_waitcnt vmcnt(2)
	ds_write_b128 v2, v[26:29]
	v_mul_lo_u32 v2, v48, s16
	v_lshl_add_u32 v2, v49, 4, v2
	s_waitcnt vmcnt(1)
	ds_write_b128 v2, v[30:33]
	v_add_u32_e32 v2, 0x1000, v0
	v_ashrrev_i32_e32 v3, 31, v2
	v_lshrrev_b32_e32 v3, 25, v3
	v_add_u32_e32 v3, v2, v3
	v_ashrrev_i32_e32 v34, 7, v3
	v_and_b32_e32 v3, 0xfffff80, v3
	v_sub_u32_e32 v35, v2, v3
	v_lshlrev_b32_e32 v2, 3, v2
	v_ashrrev_i32_e32 v3, 31, v2
	v_lshl_add_u64 v[2:3], v[2:3], 1, s[0:1]
	global_load_dwordx4 v[2:5], v[2:3], off
	v_ashrrev_i32_e32 v23, 31, v22
	global_load_dwordx4 v[10:13], v[10:11], off
	v_ashrrev_i32_e32 v15, 31, v14
	v_ashrrev_i32_e32 v42, 7, v19
	v_and_b32_e32 v19, 0xfffff80, v19
	v_lshrrev_b32_e32 v23, 25, v23
	v_add_u32_e32 v26, 0x1c00, v0
	v_lshl_add_u64 v[14:15], v[14:15], 1, s[0:1]
	v_sub_u32_e32 v43, v18, v19
	v_lshlrev_b32_e32 v18, 3, v18
	v_add_u32_e32 v23, v22, v23
	v_ashrrev_i32_e32 v27, 31, v26
	global_load_dwordx4 v[14:17], v[14:15], off
	v_ashrrev_i32_e32 v19, 31, v18
	v_ashrrev_i32_e32 v44, 7, v23
	v_and_b32_e32 v23, 0xfffff80, v23
	v_lshrrev_b32_e32 v27, 25, v27
	v_add_u32_e32 v30, 0x1e00, v0
	v_lshl_add_u64 v[18:19], v[18:19], 1, s[0:1]
	v_sub_u32_e32 v45, v22, v23
	v_lshlrev_b32_e32 v22, 3, v22
	v_add_u32_e32 v27, v26, v27
	v_ashrrev_i32_e32 v31, 31, v30
	global_load_dwordx4 v[18:21], v[18:19], off
	v_ashrrev_i32_e32 v23, 31, v22
	v_ashrrev_i32_e32 v46, 7, v27
	v_and_b32_e32 v27, 0xfffff80, v27
	v_lshrrev_b32_e32 v31, 25, v31
	v_lshl_add_u64 v[22:23], v[22:23], 1, s[0:1]
	v_sub_u32_e32 v47, v26, v27
	v_lshlrev_b32_e32 v26, 3, v26
	v_add_u32_e32 v31, v30, v31
	global_load_dwordx4 v[22:25], v[22:23], off
	v_ashrrev_i32_e32 v27, 31, v26
	v_ashrrev_i32_e32 v48, 7, v31
	v_and_b32_e32 v31, 0xfffff80, v31
	v_lshl_add_u64 v[26:27], v[26:27], 1, s[0:1]
	v_sub_u32_e32 v49, v30, v31
	v_lshlrev_b32_e32 v30, 3, v30
	global_load_dwordx4 v[26:29], v[26:27], off
	v_ashrrev_i32_e32 v31, 31, v30
	v_lshl_add_u64 v[30:31], v[30:31], 1, s[0:1]
	global_load_dwordx4 v[30:33], v[30:31], off
	v_mul_lo_u32 v34, v34, s16
	v_lshl_add_u32 v34, v35, 4, v34
	s_waitcnt vmcnt(6)
	ds_write_b128 v34, v[2:5]
	v_mul_lo_u32 v2, v36, s16
	v_lshl_add_u32 v2, v37, 4, v2
	ds_write_b128 v2, v[6:9]
	v_mul_lo_u32 v2, v38, s16
	v_lshl_add_u32 v2, v39, 4, v2
	s_waitcnt vmcnt(5)
	ds_write_b128 v2, v[10:13]
	v_mul_lo_u32 v2, v40, s16
	v_lshl_add_u32 v2, v41, 4, v2
	s_waitcnt vmcnt(4)
	ds_write_b128 v2, v[14:17]
	v_mul_lo_u32 v2, v42, s16
	v_lshl_add_u32 v2, v43, 4, v2
	s_waitcnt vmcnt(3)
	ds_write_b128 v2, v[18:21]
	v_mul_lo_u32 v2, v44, s16
	v_lshl_add_u32 v2, v45, 4, v2
	s_waitcnt vmcnt(2)
	ds_write_b128 v2, v[22:25]
	v_mul_lo_u32 v2, v46, s16
	v_lshl_add_u32 v2, v47, 4, v2
	s_waitcnt vmcnt(1)
	ds_write_b128 v2, v[26:29]
	v_mul_lo_u32 v2, v48, s16
	v_lshl_add_u32 v2, v49, 4, v2
	s_waitcnt vmcnt(0)
	ds_write_b128 v2, v[30:33]
	s_waitcnt lgkmcnt(0)
	s_barrier
	s_cbranch_scc1 .LBB0_860
	s_lshl_b32 s29, s84, 4
	s_cmpk_gt_u32 s84, 0xfd
	s_cselect_b64 s[0:1], -1, 0
	s_add_i32 s64, s66, 0xffffc080
	s_lshl_b64 s[2:3], s[64:65], 9
	s_add_u32 s6, s31, s2
	s_addc_u32 s7, s37, s3
	s_add_u32 s8, s55, s2
	s_addc_u32 s9, s70, s3
	s_cmpk_gt_u32 s84, 0xf7
	s_cselect_b64 s[56:57], -1, 0
	s_add_i32 s64, s66, 0xffffc200
	s_lshl_b64 s[2:3], s[64:65], 11
	s_add_u32 s60, s71, s2
	v_lshrrev_b32_e32 v3, 1, v0
	s_movk_i32 s10, 0x810
	s_addc_u32 s61, s72, s3
	v_and_b32_e32 v2, 31, v0
	v_and_b32_e32 v3, 16, v3
	v_and_b32_e32 v0, 63, v0
	s_add_u32 s68, s73, s2
	v_mad_u32_u24 v72, v2, s10, v3
	v_lshlrev_b32_e32 v2, 4, v0
	v_mov_b32_e32 v3, v1
	s_addc_u32 s69, s74, s3
	v_lshl_add_u64 v[66:67], s[90:91], 0, v[2:3]
	v_add_u32_e32 v73, 0x10200, v72
	s_lshl_b32 s52, s84, 15
	s_sub_i32 s53, s66, 48
	s_lshl_b32 s62, s84, 13
	s_sub_i32 s63, s29, 24
	s_bitcmp1_b32 s28, 2
	s_cbranch_scc0 .Lstg_a2
	s_sleep 127
	s_sleep 127
.Lstg_a2:
	s_branch .LBB0_889
.LBB0_888:
	s_add_i32 s2, s28, 8
	s_cmp_lt_i32 s28, 60
	s_mov_b32 s28, s2
	s_cbranch_scc0 .LBB0_859
